# K-loop back edge rotated: per-iteration SALU moved before the closing barrier, private barrier on exit path
# baseline (speedup 1.0000x reference)
.LBB0_246:
	s_andn2_b64 vcc, exec, s[18:19]
	s_cbranch_vccnz .Lk_zero_skip
	s_add_u32 s44, s44, 0x80
	s_addc_u32 s45, s45, 0
	s_add_u32 s23, s46, 0x100
	s_addc_u32 s48, s47, 0
	s_mov_b32 s46, 0
	s_add_i32 s49, s46, 2
	s_add_u32 s69, s44, 0x80
	s_addc_u32 s47, s45, 0
	s_add_i32 s80, 0, 0x10000
	s_cmp_eq_u32 s90, s46
	s_cselect_b32 s47, s65, s47
	s_cselect_b32 s46, s64, s69
	s_cselect_b32 s71, s67, s48
	s_cselect_b32 s70, s66, s23
	s_add_i32 s69, 0, 0x14000
	v_add_u32_e32 v140, s80, v227
	v_add_u32_e32 v152, s69, v227
	ds_read_b128 v[128:131], v140
	ds_read_b128 v[132:135], v140 offset:1024
	ds_read_b128 v[136:139], v140 offset:2048
	ds_read_b128 v[140:143], v140 offset:3072
	ds_read_b128 v[144:147], v152
	ds_read_b128 v[148:151], v152 offset:1024
	ds_read_b128 v[174:177], v152 offset:2048
	ds_read_b128 v[178:181], v152 offset:3072
	v_lshl_add_u64 v[210:211], s[44:45], 0, v[170:171]
	s_add_i32 m0, s50, 0xc000
	ds_read_b128 v[182:185], v230
	ds_read_b128 v[186:189], v230 offset:1024
	ds_read_b128 v[190:193], v230 offset:2048
	ds_read_b128 v[194:197], v230 offset:3072
	ds_read_b128 v[198:201], v230 offset:4096
	ds_read_b128 v[202:205], v230 offset:5120
	ds_read_b128 v[206:209], v230 offset:6144
	ds_read_b128 v[232:235], v230 offset:7168
	global_load_lds_dwordx4 v[210:211], off
	v_lshl_add_u64 v[210:211], s[44:45], 0, v[172:173]
	s_add_i32 m0, s50, 0xe000
	s_nop 0
	global_load_lds_dwordx4 v[210:211], off
	s_waitcnt vmcnt(8)
	s_waitcnt lgkmcnt(0)
	s_barrier
	s_setprio 1
	s_waitcnt lgkmcnt(0)
	v_mfma_f32_16x16x32_bf16 v[16:19], v[128:131], v[182:185], 0
	v_mfma_f32_16x16x32_bf16 v[28:31], v[136:139], v[182:185], 0
	v_mfma_f32_16x16x32_bf16 v[12:15], v[128:131], v[190:193], 0
	v_mfma_f32_16x16x32_bf16 v[8:11], v[136:139], v[190:193], 0
	v_mfma_f32_16x16x32_bf16 v[124:127], v[128:131], v[198:201], 0
	v_mfma_f32_16x16x32_bf16 v[120:123], v[136:139], v[198:201], 0
	v_mfma_f32_16x16x32_bf16 v[108:111], v[128:131], v[206:209], 0
	v_mfma_f32_16x16x32_bf16 v[104:107], v[136:139], v[206:209], 0
	v_mfma_f32_16x16x32_bf16 v[16:19], v[132:135], v[186:189], v[16:19]
	v_mfma_f32_16x16x32_bf16 v[28:31], v[140:143], v[186:189], v[28:31]
	v_mfma_f32_16x16x32_bf16 v[12:15], v[132:135], v[194:197], v[12:15]
	v_mfma_f32_16x16x32_bf16 v[8:11], v[140:143], v[194:197], v[8:11]
	v_mfma_f32_16x16x32_bf16 v[124:127], v[132:135], v[202:205], v[124:127]
	v_mfma_f32_16x16x32_bf16 v[120:123], v[140:143], v[202:205], v[120:123]
	v_mfma_f32_16x16x32_bf16 v[108:111], v[132:135], v[232:235], v[108:111]
	v_mfma_f32_16x16x32_bf16 v[104:107], v[140:143], v[232:235], v[104:107]
	s_setprio 0
	s_setprio 1
	v_mfma_f32_16x16x32_bf16 v[24:27], v[144:147], v[182:185], 0
	v_mfma_f32_16x16x32_bf16 v[20:23], v[174:177], v[182:185], 0
	v_mfma_f32_16x16x32_bf16 v[4:7], v[144:147], v[190:193], 0
	v_mfma_f32_16x16x32_bf16 v[0:3], v[174:177], v[190:193], 0
	v_mfma_f32_16x16x32_bf16 v[116:119], v[144:147], v[198:201], 0
	v_mfma_f32_16x16x32_bf16 v[112:115], v[174:177], v[198:201], 0
	v_mfma_f32_16x16x32_bf16 v[100:103], v[144:147], v[206:209], 0
	v_mfma_f32_16x16x32_bf16 v[96:99], v[174:177], v[206:209], 0
	v_mfma_f32_16x16x32_bf16 v[24:27], v[148:151], v[186:189], v[24:27]
	v_mfma_f32_16x16x32_bf16 v[20:23], v[178:181], v[186:189], v[20:23]
	v_mfma_f32_16x16x32_bf16 v[4:7], v[148:151], v[194:197], v[4:7]
	v_mfma_f32_16x16x32_bf16 v[0:3], v[178:181], v[194:197], v[0:3]
	v_mfma_f32_16x16x32_bf16 v[116:119], v[148:151], v[202:205], v[116:119]
	v_mfma_f32_16x16x32_bf16 v[112:115], v[178:181], v[202:205], v[112:115]
	v_mfma_f32_16x16x32_bf16 v[100:103], v[148:151], v[232:235], v[100:103]
	v_mfma_f32_16x16x32_bf16 v[96:99], v[178:181], v[232:235], v[96:99]
	s_setprio 0
	s_barrier
	s_add_i32 s80, s80, s3
	v_lshl_add_u64 v[210:211], s[70:71], 0, v[160:161]
	s_mov_b32 m0, s80
	ds_read_b128 v[182:185], v230 offset:16384
	ds_read_b128 v[186:189], v230 offset:17408
	ds_read_b128 v[190:193], v230 offset:18432
	ds_read_b128 v[194:197], v230 offset:19456
	ds_read_b128 v[198:201], v230 offset:20480
	ds_read_b128 v[202:205], v230 offset:21504
	ds_read_b128 v[206:209], v230 offset:22528
	ds_read_b128 v[232:235], v230 offset:23552
	global_load_lds_dwordx4 v[210:211], off
	s_add_i32 m0, s80, 0x2000
	v_lshl_add_u64 v[236:237], s[70:71], 0, v[164:165]
	s_add_u32 s70, s70, s26
	s_addc_u32 s71, s71, 0
	s_add_i32 s69, s69, s3
	global_load_lds_dwordx4 v[236:237], off
	v_lshl_add_u64 v[238:239], s[70:71], 0, v[160:161]
	s_mov_b32 m0, s69
	v_lshl_add_u64 v[240:241], s[70:71], 0, v[164:165]
	global_load_lds_dwordx4 v[238:239], off
	s_add_i32 m0, s69, 0x2000
	v_lshl_add_u64 v[242:243], s[46:47], 0, v[158:159]
	global_load_lds_dwordx4 v[240:241], off
	s_mov_b32 m0, s50
	v_lshl_add_u64 v[244:245], s[46:47], 0, v[162:163]
	global_load_lds_dwordx4 v[242:243], off
	s_mov_b32 m0, s51
	s_nop 0
	global_load_lds_dwordx4 v[244:245], off
	s_waitcnt vmcnt(8)
	s_waitcnt lgkmcnt(0)
	s_barrier
	s_setprio 1
	s_waitcnt lgkmcnt(0)
	v_mfma_f32_16x16x32_bf16 v[92:95], v[128:131], v[182:185], 0
	v_mfma_f32_16x16x32_bf16 v[88:91], v[136:139], v[182:185], 0
	v_mfma_f32_16x16x32_bf16 v[76:79], v[128:131], v[190:193], 0
	v_mfma_f32_16x16x32_bf16 v[72:75], v[136:139], v[190:193], 0
	v_mfma_f32_16x16x32_bf16 v[60:63], v[128:131], v[198:201], 0
	v_mfma_f32_16x16x32_bf16 v[56:59], v[136:139], v[198:201], 0
	v_mfma_f32_16x16x32_bf16 v[44:47], v[128:131], v[206:209], 0
	v_mfma_f32_16x16x32_bf16 v[40:43], v[136:139], v[206:209], 0
	v_mfma_f32_16x16x32_bf16 v[92:95], v[132:135], v[186:189], v[92:95]
	v_mfma_f32_16x16x32_bf16 v[88:91], v[140:143], v[186:189], v[88:91]
	v_mfma_f32_16x16x32_bf16 v[76:79], v[132:135], v[194:197], v[76:79]
	v_mfma_f32_16x16x32_bf16 v[72:75], v[140:143], v[194:197], v[72:75]
	v_mfma_f32_16x16x32_bf16 v[60:63], v[132:135], v[202:205], v[60:63]
	v_mfma_f32_16x16x32_bf16 v[56:59], v[140:143], v[202:205], v[56:59]
	v_mfma_f32_16x16x32_bf16 v[44:47], v[132:135], v[232:235], v[44:47]
	v_mfma_f32_16x16x32_bf16 v[40:43], v[140:143], v[232:235], v[40:43]
	s_setprio 0
	s_setprio 1
	v_mfma_f32_16x16x32_bf16 v[84:87], v[144:147], v[182:185], 0
	v_mfma_f32_16x16x32_bf16 v[80:83], v[174:177], v[182:185], 0
	v_mfma_f32_16x16x32_bf16 v[68:71], v[144:147], v[190:193], 0
	v_mfma_f32_16x16x32_bf16 v[64:67], v[174:177], v[190:193], 0
	v_mfma_f32_16x16x32_bf16 v[52:55], v[144:147], v[198:201], 0
	v_mfma_f32_16x16x32_bf16 v[48:51], v[174:177], v[198:201], 0
	v_mfma_f32_16x16x32_bf16 v[36:39], v[144:147], v[206:209], 0
	v_mfma_f32_16x16x32_bf16 v[32:35], v[174:177], v[206:209], 0
	v_mfma_f32_16x16x32_bf16 v[84:87], v[148:151], v[186:189], v[84:87]
	v_mfma_f32_16x16x32_bf16 v[80:83], v[178:181], v[186:189], v[80:83]
	v_mfma_f32_16x16x32_bf16 v[68:71], v[148:151], v[194:197], v[68:71]
	v_mfma_f32_16x16x32_bf16 v[64:67], v[178:181], v[194:197], v[64:67]
	v_mfma_f32_16x16x32_bf16 v[52:55], v[148:151], v[202:205], v[52:55]
	v_mfma_f32_16x16x32_bf16 v[48:51], v[178:181], v[202:205], v[48:51]
	v_mfma_f32_16x16x32_bf16 v[36:39], v[148:151], v[232:235], v[36:39]
	v_mfma_f32_16x16x32_bf16 v[32:35], v[178:181], v[232:235], v[32:35]
	s_setprio 0
	s_barrier
	s_add_i32 s69, 0, 0x18000
	s_add_i32 s70, 0, 0x1c000
	v_add_u32_e32 v140, s69, v227
	v_add_u32_e32 v152, s70, v227
	ds_read_b128 v[128:131], v140
	ds_read_b128 v[132:135], v140 offset:1024
	ds_read_b128 v[136:139], v140 offset:2048
	ds_read_b128 v[140:143], v140 offset:3072
	ds_read_b128 v[144:147], v152
	ds_read_b128 v[148:151], v152 offset:1024
	ds_read_b128 v[174:177], v152 offset:2048
	ds_read_b128 v[178:181], v152 offset:3072
	s_add_u32 s46, s46, s26
	s_addc_u32 s47, s47, 0
	s_mov_b32 m0, s8
	v_lshl_add_u64 v[246:247], s[46:47], 0, v[158:159]
	ds_read_b128 v[182:185], v230 offset:32768
	ds_read_b128 v[186:189], v230 offset:33792
	ds_read_b128 v[190:193], v230 offset:34816
	ds_read_b128 v[194:197], v230 offset:35840
	ds_read_b128 v[198:201], v230 offset:36864
	ds_read_b128 v[202:205], v230 offset:37888
	ds_read_b128 v[206:209], v230 offset:38912
	ds_read_b128 v[232:235], v230 offset:39936
	global_load_lds_dwordx4 v[246:247], off
	v_lshl_add_u64 v[246:247], s[46:47], 0, v[162:163]
	s_mov_b32 m0, s9
	s_nop 0
	global_load_lds_dwordx4 v[246:247], off
	s_waitcnt vmcnt(8)
	s_waitcnt lgkmcnt(0)
	s_barrier
	s_setprio 1
	s_waitcnt lgkmcnt(0)
	v_mfma_f32_16x16x32_bf16 v[16:19], v[128:131], v[182:185], v[16:19]
	v_mfma_f32_16x16x32_bf16 v[28:31], v[136:139], v[182:185], v[28:31]
	v_mfma_f32_16x16x32_bf16 v[12:15], v[128:131], v[190:193], v[12:15]
	v_mfma_f32_16x16x32_bf16 v[8:11], v[136:139], v[190:193], v[8:11]
	v_mfma_f32_16x16x32_bf16 v[124:127], v[128:131], v[198:201], v[124:127]
	v_mfma_f32_16x16x32_bf16 v[120:123], v[136:139], v[198:201], v[120:123]
	v_mfma_f32_16x16x32_bf16 v[108:111], v[128:131], v[206:209], v[108:111]
	v_mfma_f32_16x16x32_bf16 v[104:107], v[136:139], v[206:209], v[104:107]
	v_mfma_f32_16x16x32_bf16 v[16:19], v[132:135], v[186:189], v[16:19]
	v_mfma_f32_16x16x32_bf16 v[28:31], v[140:143], v[186:189], v[28:31]
	v_mfma_f32_16x16x32_bf16 v[12:15], v[132:135], v[194:197], v[12:15]
	v_mfma_f32_16x16x32_bf16 v[8:11], v[140:143], v[194:197], v[8:11]
	v_mfma_f32_16x16x32_bf16 v[124:127], v[132:135], v[202:205], v[124:127]
	v_mfma_f32_16x16x32_bf16 v[120:123], v[140:143], v[202:205], v[120:123]
	v_mfma_f32_16x16x32_bf16 v[108:111], v[132:135], v[232:235], v[108:111]
	v_mfma_f32_16x16x32_bf16 v[104:107], v[140:143], v[232:235], v[104:107]
	s_setprio 0
	s_setprio 1
	v_mfma_f32_16x16x32_bf16 v[24:27], v[144:147], v[182:185], v[24:27]
	v_mfma_f32_16x16x32_bf16 v[20:23], v[174:177], v[182:185], v[20:23]
	v_mfma_f32_16x16x32_bf16 v[4:7], v[144:147], v[190:193], v[4:7]
	v_mfma_f32_16x16x32_bf16 v[0:3], v[174:177], v[190:193], v[0:3]
	v_mfma_f32_16x16x32_bf16 v[116:119], v[144:147], v[198:201], v[116:119]
	v_mfma_f32_16x16x32_bf16 v[112:115], v[174:177], v[198:201], v[112:115]
	v_mfma_f32_16x16x32_bf16 v[100:103], v[144:147], v[206:209], v[100:103]
	v_mfma_f32_16x16x32_bf16 v[96:99], v[174:177], v[206:209], v[96:99]
	v_mfma_f32_16x16x32_bf16 v[24:27], v[148:151], v[186:189], v[24:27]
	v_mfma_f32_16x16x32_bf16 v[20:23], v[178:181], v[186:189], v[20:23]
	v_mfma_f32_16x16x32_bf16 v[4:7], v[148:151], v[194:197], v[4:7]
	v_mfma_f32_16x16x32_bf16 v[0:3], v[178:181], v[194:197], v[0:3]
	v_mfma_f32_16x16x32_bf16 v[116:119], v[148:151], v[202:205], v[116:119]
	v_mfma_f32_16x16x32_bf16 v[112:115], v[178:181], v[202:205], v[112:115]
	v_mfma_f32_16x16x32_bf16 v[100:103], v[148:151], v[232:235], v[100:103]
	v_mfma_f32_16x16x32_bf16 v[96:99], v[178:181], v[232:235], v[96:99]
	s_setprio 0
	s_barrier
	s_add_i32 s46, s69, s3
	v_lshl_add_u64 v[210:211], v[210:211], 0, s[6:7]
	s_mov_b32 m0, s46
	ds_read_b128 v[182:185], v230 offset:49152
	ds_read_b128 v[186:189], v230 offset:50176
	ds_read_b128 v[190:193], v230 offset:51200
	ds_read_b128 v[194:197], v230 offset:52224
	ds_read_b128 v[198:201], v230 offset:53248
	ds_read_b128 v[202:205], v230 offset:54272
	ds_read_b128 v[206:209], v230 offset:55296
	ds_read_b128 v[232:235], v230 offset:56320
	global_load_lds_dwordx4 v[210:211], off
	v_lshl_add_u64 v[210:211], v[236:237], 0, s[6:7]
	s_add_i32 m0, s46, 0x2000
	s_add_i32 s46, s70, s3
	global_load_lds_dwordx4 v[210:211], off
	v_lshl_add_u64 v[210:211], v[238:239], 0, s[6:7]
	s_mov_b32 m0, s46
	s_nop 0
	global_load_lds_dwordx4 v[210:211], off
	v_lshl_add_u64 v[210:211], v[240:241], 0, s[6:7]
	s_add_i32 m0, s46, 0x2000
	s_nop 0
	global_load_lds_dwordx4 v[210:211], off
	v_lshl_add_u64 v[210:211], v[242:243], 0, s[6:7]
	s_mov_b32 m0, s30
	s_nop 0
	global_load_lds_dwordx4 v[210:211], off
	v_lshl_add_u64 v[210:211], v[244:245], 0, s[6:7]
	s_mov_b32 m0, s31
	s_nop 0
	global_load_lds_dwordx4 v[210:211], off
	s_waitcnt vmcnt(8)
	s_waitcnt lgkmcnt(0)
	s_barrier
	s_setprio 1
	s_waitcnt lgkmcnt(0)
	v_mfma_f32_16x16x32_bf16 v[92:95], v[128:131], v[182:185], v[92:95]
	v_mfma_f32_16x16x32_bf16 v[88:91], v[136:139], v[182:185], v[88:91]
	v_mfma_f32_16x16x32_bf16 v[76:79], v[128:131], v[190:193], v[76:79]
	v_mfma_f32_16x16x32_bf16 v[72:75], v[136:139], v[190:193], v[72:75]
	v_mfma_f32_16x16x32_bf16 v[60:63], v[128:131], v[198:201], v[60:63]
	v_mfma_f32_16x16x32_bf16 v[56:59], v[136:139], v[198:201], v[56:59]
	v_mfma_f32_16x16x32_bf16 v[44:47], v[128:131], v[206:209], v[44:47]
	v_mfma_f32_16x16x32_bf16 v[40:43], v[136:139], v[206:209], v[40:43]
	v_mfma_f32_16x16x32_bf16 v[92:95], v[132:135], v[186:189], v[92:95]
	v_mfma_f32_16x16x32_bf16 v[88:91], v[140:143], v[186:189], v[88:91]
	v_mfma_f32_16x16x32_bf16 v[76:79], v[132:135], v[194:197], v[76:79]
	v_mfma_f32_16x16x32_bf16 v[72:75], v[140:143], v[194:197], v[72:75]
	v_mfma_f32_16x16x32_bf16 v[60:63], v[132:135], v[202:205], v[60:63]
	v_mfma_f32_16x16x32_bf16 v[56:59], v[140:143], v[202:205], v[56:59]
	v_mfma_f32_16x16x32_bf16 v[44:47], v[132:135], v[232:235], v[44:47]
	v_mfma_f32_16x16x32_bf16 v[40:43], v[140:143], v[232:235], v[40:43]
	s_setprio 0
	s_setprio 1
	v_mfma_f32_16x16x32_bf16 v[84:87], v[144:147], v[182:185], v[84:87]
	v_mfma_f32_16x16x32_bf16 v[80:83], v[174:177], v[182:185], v[80:83]
	v_mfma_f32_16x16x32_bf16 v[68:71], v[144:147], v[190:193], v[68:71]
	v_mfma_f32_16x16x32_bf16 v[64:67], v[174:177], v[190:193], v[64:67]
	v_mfma_f32_16x16x32_bf16 v[52:55], v[144:147], v[198:201], v[52:55]
	v_mfma_f32_16x16x32_bf16 v[48:51], v[174:177], v[198:201], v[48:51]
	v_mfma_f32_16x16x32_bf16 v[36:39], v[144:147], v[206:209], v[36:39]
	v_mfma_f32_16x16x32_bf16 v[32:35], v[174:177], v[206:209], v[32:35]
	v_mfma_f32_16x16x32_bf16 v[84:87], v[148:151], v[186:189], v[84:87]
	v_mfma_f32_16x16x32_bf16 v[80:83], v[178:181], v[186:189], v[80:83]
	v_mfma_f32_16x16x32_bf16 v[68:71], v[148:151], v[194:197], v[68:71]
	v_mfma_f32_16x16x32_bf16 v[64:67], v[178:181], v[194:197], v[64:67]
	v_mfma_f32_16x16x32_bf16 v[52:55], v[148:151], v[202:205], v[52:55]
	v_mfma_f32_16x16x32_bf16 v[48:51], v[178:181], v[202:205], v[48:51]
	v_mfma_f32_16x16x32_bf16 v[36:39], v[148:151], v[232:235], v[36:39]
	v_mfma_f32_16x16x32_bf16 v[32:35], v[178:181], v[232:235], v[32:35]
	s_add_u32 s44, s44, 0x100
	s_addc_u32 s45, s45, 0
	s_add_u32 s23, s23, 0x100
	s_addc_u32 s48, s48, 0
	s_cmp_ge_u32 s49, s88
	s_mov_b32 s46, s49
	s_cbranch_scc1 .Lk_exit
	s_add_i32 s49, s46, 2
	s_add_u32 s69, s44, 0x80
	s_addc_u32 s47, s45, 0
	s_add_i32 s80, 0, 0x10000
	s_cmp_eq_u32 s90, s46
	s_cselect_b32 s47, s65, s47
	s_cselect_b32 s46, s64, s69
	s_cselect_b32 s71, s67, s48
	s_cselect_b32 s70, s66, s23
	s_add_i32 s69, 0, 0x14000
	s_setprio 0
	s_barrier
.LBB0_248:
	v_add_u32_e32 v140, s80, v227
	v_add_u32_e32 v152, s69, v227
	ds_read_b128 v[128:131], v140
	ds_read_b128 v[132:135], v140 offset:1024
	ds_read_b128 v[136:139], v140 offset:2048
	ds_read_b128 v[140:143], v140 offset:3072
	ds_read_b128 v[144:147], v152
	ds_read_b128 v[148:151], v152 offset:1024
	ds_read_b128 v[174:177], v152 offset:2048
	ds_read_b128 v[178:181], v152 offset:3072
	v_lshl_add_u64 v[210:211], s[44:45], 0, v[170:171]
	s_add_i32 m0, s50, 0xc000
	ds_read_b128 v[182:185], v230
	ds_read_b128 v[186:189], v230 offset:1024
	ds_read_b128 v[190:193], v230 offset:2048
	ds_read_b128 v[194:197], v230 offset:3072
	ds_read_b128 v[198:201], v230 offset:4096
	ds_read_b128 v[202:205], v230 offset:5120
	ds_read_b128 v[206:209], v230 offset:6144
	ds_read_b128 v[232:235], v230 offset:7168
	global_load_lds_dwordx4 v[210:211], off
	v_lshl_add_u64 v[210:211], s[44:45], 0, v[172:173]
	s_add_i32 m0, s50, 0xe000
	s_nop 0
	global_load_lds_dwordx4 v[210:211], off
	s_waitcnt vmcnt(8)
	s_waitcnt lgkmcnt(0)
	s_barrier
	s_setprio 1
	s_waitcnt lgkmcnt(0)
	v_mfma_f32_16x16x32_bf16 v[16:19], v[128:131], v[182:185], v[16:19]
	v_mfma_f32_16x16x32_bf16 v[28:31], v[136:139], v[182:185], v[28:31]
	v_mfma_f32_16x16x32_bf16 v[12:15], v[128:131], v[190:193], v[12:15]
	v_mfma_f32_16x16x32_bf16 v[8:11], v[136:139], v[190:193], v[8:11]
	v_mfma_f32_16x16x32_bf16 v[124:127], v[128:131], v[198:201], v[124:127]
	v_mfma_f32_16x16x32_bf16 v[120:123], v[136:139], v[198:201], v[120:123]
	v_mfma_f32_16x16x32_bf16 v[108:111], v[128:131], v[206:209], v[108:111]
	v_mfma_f32_16x16x32_bf16 v[104:107], v[136:139], v[206:209], v[104:107]
	v_mfma_f32_16x16x32_bf16 v[16:19], v[132:135], v[186:189], v[16:19]
	v_mfma_f32_16x16x32_bf16 v[28:31], v[140:143], v[186:189], v[28:31]
	v_mfma_f32_16x16x32_bf16 v[12:15], v[132:135], v[194:197], v[12:15]
	v_mfma_f32_16x16x32_bf16 v[8:11], v[140:143], v[194:197], v[8:11]
	v_mfma_f32_16x16x32_bf16 v[124:127], v[132:135], v[202:205], v[124:127]
	v_mfma_f32_16x16x32_bf16 v[120:123], v[140:143], v[202:205], v[120:123]
	v_mfma_f32_16x16x32_bf16 v[108:111], v[132:135], v[232:235], v[108:111]
	v_mfma_f32_16x16x32_bf16 v[104:107], v[140:143], v[232:235], v[104:107]
	s_setprio 0
	s_setprio 1
	v_mfma_f32_16x16x32_bf16 v[24:27], v[144:147], v[182:185], v[24:27]
	v_mfma_f32_16x16x32_bf16 v[20:23], v[174:177], v[182:185], v[20:23]
	v_mfma_f32_16x16x32_bf16 v[4:7], v[144:147], v[190:193], v[4:7]
	v_mfma_f32_16x16x32_bf16 v[0:3], v[174:177], v[190:193], v[0:3]
	v_mfma_f32_16x16x32_bf16 v[116:119], v[144:147], v[198:201], v[116:119]
	v_mfma_f32_16x16x32_bf16 v[112:115], v[174:177], v[198:201], v[112:115]
	v_mfma_f32_16x16x32_bf16 v[100:103], v[144:147], v[206:209], v[100:103]
	v_mfma_f32_16x16x32_bf16 v[96:99], v[174:177], v[206:209], v[96:99]
	v_mfma_f32_16x16x32_bf16 v[24:27], v[148:151], v[186:189], v[24:27]
	v_mfma_f32_16x16x32_bf16 v[20:23], v[178:181], v[186:189], v[20:23]
	v_mfma_f32_16x16x32_bf16 v[4:7], v[148:151], v[194:197], v[4:7]
	v_mfma_f32_16x16x32_bf16 v[0:3], v[178:181], v[194:197], v[0:3]
	v_mfma_f32_16x16x32_bf16 v[116:119], v[148:151], v[202:205], v[116:119]
	v_mfma_f32_16x16x32_bf16 v[112:115], v[178:181], v[202:205], v[112:115]
	v_mfma_f32_16x16x32_bf16 v[100:103], v[148:151], v[232:235], v[100:103]
	v_mfma_f32_16x16x32_bf16 v[96:99], v[178:181], v[232:235], v[96:99]
	s_setprio 0
	s_barrier
	s_add_i32 s80, s80, s3
	v_lshl_add_u64 v[210:211], s[70:71], 0, v[160:161]
	s_mov_b32 m0, s80
	ds_read_b128 v[182:185], v230 offset:16384
	ds_read_b128 v[186:189], v230 offset:17408
	ds_read_b128 v[190:193], v230 offset:18432
	ds_read_b128 v[194:197], v230 offset:19456
	ds_read_b128 v[198:201], v230 offset:20480
	ds_read_b128 v[202:205], v230 offset:21504
	ds_read_b128 v[206:209], v230 offset:22528
	ds_read_b128 v[232:235], v230 offset:23552
	global_load_lds_dwordx4 v[210:211], off
	s_add_i32 m0, s80, 0x2000
	v_lshl_add_u64 v[236:237], s[70:71], 0, v[164:165]
	s_add_u32 s70, s70, s26
	s_addc_u32 s71, s71, 0
	s_add_i32 s69, s69, s3
	global_load_lds_dwordx4 v[236:237], off
	v_lshl_add_u64 v[238:239], s[70:71], 0, v[160:161]
	s_mov_b32 m0, s69
	v_lshl_add_u64 v[240:241], s[70:71], 0, v[164:165]
	global_load_lds_dwordx4 v[238:239], off
	s_add_i32 m0, s69, 0x2000
	v_lshl_add_u64 v[242:243], s[46:47], 0, v[158:159]
	global_load_lds_dwordx4 v[240:241], off
	s_mov_b32 m0, s50
	v_lshl_add_u64 v[244:245], s[46:47], 0, v[162:163]
	global_load_lds_dwordx4 v[242:243], off
	s_mov_b32 m0, s51
	s_nop 0
	global_load_lds_dwordx4 v[244:245], off
	s_waitcnt vmcnt(8)
	s_waitcnt lgkmcnt(0)
	s_barrier
	s_setprio 1
	s_waitcnt lgkmcnt(0)
	v_mfma_f32_16x16x32_bf16 v[92:95], v[128:131], v[182:185], v[92:95]
	v_mfma_f32_16x16x32_bf16 v[88:91], v[136:139], v[182:185], v[88:91]
	v_mfma_f32_16x16x32_bf16 v[76:79], v[128:131], v[190:193], v[76:79]
	v_mfma_f32_16x16x32_bf16 v[72:75], v[136:139], v[190:193], v[72:75]
	v_mfma_f32_16x16x32_bf16 v[60:63], v[128:131], v[198:201], v[60:63]
	v_mfma_f32_16x16x32_bf16 v[56:59], v[136:139], v[198:201], v[56:59]
	v_mfma_f32_16x16x32_bf16 v[44:47], v[128:131], v[206:209], v[44:47]
	v_mfma_f32_16x16x32_bf16 v[40:43], v[136:139], v[206:209], v[40:43]
	v_mfma_f32_16x16x32_bf16 v[92:95], v[132:135], v[186:189], v[92:95]
	v_mfma_f32_16x16x32_bf16 v[88:91], v[140:143], v[186:189], v[88:91]
	v_mfma_f32_16x16x32_bf16 v[76:79], v[132:135], v[194:197], v[76:79]
	v_mfma_f32_16x16x32_bf16 v[72:75], v[140:143], v[194:197], v[72:75]
	v_mfma_f32_16x16x32_bf16 v[60:63], v[132:135], v[202:205], v[60:63]
	v_mfma_f32_16x16x32_bf16 v[56:59], v[140:143], v[202:205], v[56:59]
	v_mfma_f32_16x16x32_bf16 v[44:47], v[132:135], v[232:235], v[44:47]
	v_mfma_f32_16x16x32_bf16 v[40:43], v[140:143], v[232:235], v[40:43]
	s_setprio 0
	s_setprio 1
	v_mfma_f32_16x16x32_bf16 v[84:87], v[144:147], v[182:185], v[84:87]
	v_mfma_f32_16x16x32_bf16 v[80:83], v[174:177], v[182:185], v[80:83]
	v_mfma_f32_16x16x32_bf16 v[68:71], v[144:147], v[190:193], v[68:71]
	v_mfma_f32_16x16x32_bf16 v[64:67], v[174:177], v[190:193], v[64:67]
	v_mfma_f32_16x16x32_bf16 v[52:55], v[144:147], v[198:201], v[52:55]
	v_mfma_f32_16x16x32_bf16 v[48:51], v[174:177], v[198:201], v[48:51]
	v_mfma_f32_16x16x32_bf16 v[36:39], v[144:147], v[206:209], v[36:39]
	v_mfma_f32_16x16x32_bf16 v[32:35], v[174:177], v[206:209], v[32:35]
	v_mfma_f32_16x16x32_bf16 v[84:87], v[148:151], v[186:189], v[84:87]
	v_mfma_f32_16x16x32_bf16 v[80:83], v[178:181], v[186:189], v[80:83]
	v_mfma_f32_16x16x32_bf16 v[68:71], v[148:151], v[194:197], v[68:71]
	v_mfma_f32_16x16x32_bf16 v[64:67], v[178:181], v[194:197], v[64:67]
	v_mfma_f32_16x16x32_bf16 v[52:55], v[148:151], v[202:205], v[52:55]
	v_mfma_f32_16x16x32_bf16 v[48:51], v[178:181], v[202:205], v[48:51]
	v_mfma_f32_16x16x32_bf16 v[36:39], v[148:151], v[232:235], v[36:39]
	v_mfma_f32_16x16x32_bf16 v[32:35], v[178:181], v[232:235], v[32:35]
	s_setprio 0
	s_barrier
	s_add_i32 s69, 0, 0x18000
	s_add_i32 s70, 0, 0x1c000
	v_add_u32_e32 v140, s69, v227
	v_add_u32_e32 v152, s70, v227
	ds_read_b128 v[128:131], v140
	ds_read_b128 v[132:135], v140 offset:1024
	ds_read_b128 v[136:139], v140 offset:2048
	ds_read_b128 v[140:143], v140 offset:3072
	ds_read_b128 v[144:147], v152
	ds_read_b128 v[148:151], v152 offset:1024
	ds_read_b128 v[174:177], v152 offset:2048
	ds_read_b128 v[178:181], v152 offset:3072
	s_add_u32 s46, s46, s26
	s_addc_u32 s47, s47, 0
	s_mov_b32 m0, s8
	v_lshl_add_u64 v[246:247], s[46:47], 0, v[158:159]
	ds_read_b128 v[182:185], v230 offset:32768
	ds_read_b128 v[186:189], v230 offset:33792
	ds_read_b128 v[190:193], v230 offset:34816
	ds_read_b128 v[194:197], v230 offset:35840
	ds_read_b128 v[198:201], v230 offset:36864
	ds_read_b128 v[202:205], v230 offset:37888
	ds_read_b128 v[206:209], v230 offset:38912
	ds_read_b128 v[232:235], v230 offset:39936
	global_load_lds_dwordx4 v[246:247], off
	v_lshl_add_u64 v[246:247], s[46:47], 0, v[162:163]
	s_mov_b32 m0, s9
	s_nop 0
	global_load_lds_dwordx4 v[246:247], off
	s_waitcnt vmcnt(8)
	s_waitcnt lgkmcnt(0)
	s_barrier
	s_setprio 1
	s_waitcnt lgkmcnt(0)
	v_mfma_f32_16x16x32_bf16 v[16:19], v[128:131], v[182:185], v[16:19]
	v_mfma_f32_16x16x32_bf16 v[28:31], v[136:139], v[182:185], v[28:31]
	v_mfma_f32_16x16x32_bf16 v[12:15], v[128:131], v[190:193], v[12:15]
	v_mfma_f32_16x16x32_bf16 v[8:11], v[136:139], v[190:193], v[8:11]
	v_mfma_f32_16x16x32_bf16 v[124:127], v[128:131], v[198:201], v[124:127]
	v_mfma_f32_16x16x32_bf16 v[120:123], v[136:139], v[198:201], v[120:123]
	v_mfma_f32_16x16x32_bf16 v[108:111], v[128:131], v[206:209], v[108:111]
	v_mfma_f32_16x16x32_bf16 v[104:107], v[136:139], v[206:209], v[104:107]
	v_mfma_f32_16x16x32_bf16 v[16:19], v[132:135], v[186:189], v[16:19]
	v_mfma_f32_16x16x32_bf16 v[28:31], v[140:143], v[186:189], v[28:31]
	v_mfma_f32_16x16x32_bf16 v[12:15], v[132:135], v[194:197], v[12:15]
	v_mfma_f32_16x16x32_bf16 v[8:11], v[140:143], v[194:197], v[8:11]
	v_mfma_f32_16x16x32_bf16 v[124:127], v[132:135], v[202:205], v[124:127]
	v_mfma_f32_16x16x32_bf16 v[120:123], v[140:143], v[202:205], v[120:123]
	v_mfma_f32_16x16x32_bf16 v[108:111], v[132:135], v[232:235], v[108:111]
	v_mfma_f32_16x16x32_bf16 v[104:107], v[140:143], v[232:235], v[104:107]
	s_setprio 0
	s_setprio 1
	v_mfma_f32_16x16x32_bf16 v[24:27], v[144:147], v[182:185], v[24:27]
	v_mfma_f32_16x16x32_bf16 v[20:23], v[174:177], v[182:185], v[20:23]
	v_mfma_f32_16x16x32_bf16 v[4:7], v[144:147], v[190:193], v[4:7]
	v_mfma_f32_16x16x32_bf16 v[0:3], v[174:177], v[190:193], v[0:3]
	v_mfma_f32_16x16x32_bf16 v[116:119], v[144:147], v[198:201], v[116:119]
	v_mfma_f32_16x16x32_bf16 v[112:115], v[174:177], v[198:201], v[112:115]
	v_mfma_f32_16x16x32_bf16 v[100:103], v[144:147], v[206:209], v[100:103]
	v_mfma_f32_16x16x32_bf16 v[96:99], v[174:177], v[206:209], v[96:99]
	v_mfma_f32_16x16x32_bf16 v[24:27], v[148:151], v[186:189], v[24:27]
	v_mfma_f32_16x16x32_bf16 v[20:23], v[178:181], v[186:189], v[20:23]
	v_mfma_f32_16x16x32_bf16 v[4:7], v[148:151], v[194:197], v[4:7]
	v_mfma_f32_16x16x32_bf16 v[0:3], v[178:181], v[194:197], v[0:3]
	v_mfma_f32_16x16x32_bf16 v[116:119], v[148:151], v[202:205], v[116:119]
	v_mfma_f32_16x16x32_bf16 v[112:115], v[178:181], v[202:205], v[112:115]
	v_mfma_f32_16x16x32_bf16 v[100:103], v[148:151], v[232:235], v[100:103]
	v_mfma_f32_16x16x32_bf16 v[96:99], v[178:181], v[232:235], v[96:99]
	s_setprio 0
	s_barrier
	s_add_i32 s46, s69, s3
	v_lshl_add_u64 v[210:211], v[210:211], 0, s[6:7]
	s_mov_b32 m0, s46
	ds_read_b128 v[182:185], v230 offset:49152
	ds_read_b128 v[186:189], v230 offset:50176
	ds_read_b128 v[190:193], v230 offset:51200
	ds_read_b128 v[194:197], v230 offset:52224
	ds_read_b128 v[198:201], v230 offset:53248
	ds_read_b128 v[202:205], v230 offset:54272
	ds_read_b128 v[206:209], v230 offset:55296
	ds_read_b128 v[232:235], v230 offset:56320
	global_load_lds_dwordx4 v[210:211], off
	v_lshl_add_u64 v[210:211], v[236:237], 0, s[6:7]
	s_add_i32 m0, s46, 0x2000
	s_add_i32 s46, s70, s3
	global_load_lds_dwordx4 v[210:211], off
	v_lshl_add_u64 v[210:211], v[238:239], 0, s[6:7]
	s_mov_b32 m0, s46
	s_nop 0
	global_load_lds_dwordx4 v[210:211], off
	v_lshl_add_u64 v[210:211], v[240:241], 0, s[6:7]
	s_add_i32 m0, s46, 0x2000
	s_nop 0
	global_load_lds_dwordx4 v[210:211], off
	v_lshl_add_u64 v[210:211], v[242:243], 0, s[6:7]
	s_mov_b32 m0, s30
	s_nop 0
	global_load_lds_dwordx4 v[210:211], off
	v_lshl_add_u64 v[210:211], v[244:245], 0, s[6:7]
	s_mov_b32 m0, s31
	s_nop 0
	global_load_lds_dwordx4 v[210:211], off
	s_waitcnt vmcnt(8)
	s_waitcnt lgkmcnt(0)
	s_barrier
	s_setprio 1
	s_waitcnt lgkmcnt(0)
	v_mfma_f32_16x16x32_bf16 v[92:95], v[128:131], v[182:185], v[92:95]
	v_mfma_f32_16x16x32_bf16 v[88:91], v[136:139], v[182:185], v[88:91]
	v_mfma_f32_16x16x32_bf16 v[76:79], v[128:131], v[190:193], v[76:79]
	v_mfma_f32_16x16x32_bf16 v[72:75], v[136:139], v[190:193], v[72:75]
	v_mfma_f32_16x16x32_bf16 v[60:63], v[128:131], v[198:201], v[60:63]
	v_mfma_f32_16x16x32_bf16 v[56:59], v[136:139], v[198:201], v[56:59]
	v_mfma_f32_16x16x32_bf16 v[44:47], v[128:131], v[206:209], v[44:47]
	v_mfma_f32_16x16x32_bf16 v[40:43], v[136:139], v[206:209], v[40:43]
	v_mfma_f32_16x16x32_bf16 v[92:95], v[132:135], v[186:189], v[92:95]
	v_mfma_f32_16x16x32_bf16 v[88:91], v[140:143], v[186:189], v[88:91]
	v_mfma_f32_16x16x32_bf16 v[76:79], v[132:135], v[194:197], v[76:79]
	v_mfma_f32_16x16x32_bf16 v[72:75], v[140:143], v[194:197], v[72:75]
	v_mfma_f32_16x16x32_bf16 v[60:63], v[132:135], v[202:205], v[60:63]
	v_mfma_f32_16x16x32_bf16 v[56:59], v[140:143], v[202:205], v[56:59]
	v_mfma_f32_16x16x32_bf16 v[44:47], v[132:135], v[232:235], v[44:47]
	v_mfma_f32_16x16x32_bf16 v[40:43], v[140:143], v[232:235], v[40:43]
	s_setprio 0
	s_setprio 1
	v_mfma_f32_16x16x32_bf16 v[84:87], v[144:147], v[182:185], v[84:87]
	v_mfma_f32_16x16x32_bf16 v[80:83], v[174:177], v[182:185], v[80:83]
	v_mfma_f32_16x16x32_bf16 v[68:71], v[144:147], v[190:193], v[68:71]
	v_mfma_f32_16x16x32_bf16 v[64:67], v[174:177], v[190:193], v[64:67]
	v_mfma_f32_16x16x32_bf16 v[52:55], v[144:147], v[198:201], v[52:55]
	v_mfma_f32_16x16x32_bf16 v[48:51], v[174:177], v[198:201], v[48:51]
	v_mfma_f32_16x16x32_bf16 v[36:39], v[144:147], v[206:209], v[36:39]
	v_mfma_f32_16x16x32_bf16 v[32:35], v[174:177], v[206:209], v[32:35]
	v_mfma_f32_16x16x32_bf16 v[84:87], v[148:151], v[186:189], v[84:87]
	v_mfma_f32_16x16x32_bf16 v[80:83], v[178:181], v[186:189], v[80:83]
	v_mfma_f32_16x16x32_bf16 v[68:71], v[148:151], v[194:197], v[68:71]
	v_mfma_f32_16x16x32_bf16 v[64:67], v[178:181], v[194:197], v[64:67]
	v_mfma_f32_16x16x32_bf16 v[52:55], v[148:151], v[202:205], v[52:55]
	v_mfma_f32_16x16x32_bf16 v[48:51], v[178:181], v[202:205], v[48:51]
	v_mfma_f32_16x16x32_bf16 v[36:39], v[148:151], v[232:235], v[36:39]
	v_mfma_f32_16x16x32_bf16 v[32:35], v[178:181], v[232:235], v[32:35]
	s_add_u32 s44, s44, 0x100
	s_addc_u32 s45, s45, 0
	s_add_u32 s23, s23, 0x100
	s_addc_u32 s48, s48, 0
	s_cmp_ge_u32 s49, s88
	s_mov_b32 s46, s49
	s_cbranch_scc1 .Lk_exit
	s_add_i32 s49, s46, 2
	s_add_u32 s69, s44, 0x80
	s_addc_u32 s47, s45, 0
	s_add_i32 s80, 0, 0x10000
	s_cmp_eq_u32 s90, s46
	s_cselect_b32 s47, s65, s47
	s_cselect_b32 s46, s64, s69
	s_cselect_b32 s71, s67, s48
	s_cselect_b32 s70, s66, s23
	s_add_i32 s69, 0, 0x14000
	s_setprio 0
	s_barrier
	s_branch .LBB0_248
.Lk_exit:
	s_setprio 0
	s_barrier
